# QKV epilogue first half: four serialized row-stat loads batched behind one wait
# speedup vs baseline: 1.0306x; 1.0010x over previous
;     __device__ __forceinline__ void row(int r, float& a, float& c) const {
;         if (st) { const f32x2v s = *(const f32x2v*)(st + 2 * (size_t)r); const float mu = s.x * (1.0f / 1024.0f), var = s.y * (1.0f / 1024.0f) - mu * mu; a = rsqrtf(var + 1e-5f); c = -a * mu; }
;         else { a = 1.0f; c = 0.0f; }
;     __device__ __forceinline__ void operator()(const f32x4 (&acc)[2][2][4][2], const Unit& u, int wr, int wc, int fr, int fq) const {
;     ...
;             for (int n = 0; n < 2; ++n) { cs[bj][n] = *(const f32x4*)(ln.cs + col0 + bj * HALF + 4 * n); bw[bj][n] = *(const f32x4*)(ln.bw + col0 + bj * HALF + 4 * n); }
; #pragma unroll
;         for (int ai = 0; ai < 2; ++ai) {
;             f16x8 rp4[4]; float ra[4], rc[4];
; #pragma unroll
;             for (int m = 0; m < 4; ++m) ln.row(row0 + ai * HALF + m * 16, ra[m], rc[m]);
; #pragma unroll
;             for (int m = 0; m < 4; ++m) { const int row = row0 + ai * HALF + m * 16;
;                 if (anyrope) rp4[m] = *(const f16x8*)(rope + (size_t)row * 32 + i0); else rp4[m] = (f16x8){1, 0, 1, 0, 1, 0, 1, 0}; }
.LBB0_597:
	v_lshl_or_b32 v190, s7, 8, v211
	v_ashrrev_i32_e32 v191, 31, v190
	v_lshlrev_b64 v[42:43], 2, v[190:191]
	v_lshl_add_u64 v[44:45], s[52:53], 0, v[42:43]
	v_lshl_add_u64 v[54:55], s[54:55], 0, v[42:43]
	global_load_dwordx4 v[78:81], v[44:45], off offset:16
	global_load_dwordx4 v[86:89], v[44:45], off
	global_load_dwordx4 v[74:77], v[54:55], off offset:16
	global_load_dwordx4 v[82:85], v[54:55], off
	global_load_dwordx4 v[46:49], v[44:45], off offset:528
	global_load_dwordx4 v[58:61], v[44:45], off offset:512
	s_nop 0
	global_load_dwordx4 v[42:45], v[54:55], off offset:528
	s_nop 0
	global_load_dwordx4 v[54:57], v[54:55], off offset:512
	v_lshl_add_u32 v192, s8, 8, v225
	v_cndmask_b32_e64 v162, 0, 1, s[26:27]
	v_ashrrev_i32_e32 v193, 31, v192
	v_or_b32_e32 v218, 16, v192
	v_cmp_ne_u32_e64 s[38:39], 1, v162
	v_ashrrev_i32_e32 v219, 31, v218
	v_or_b32_e32 v204, 32, v192
	v_ashrrev_i32_e32 v205, 31, v204
	v_or_b32_e32 v198, 48, v192
	v_ashrrev_i32_e32 v199, 31, v198
	v_mov_b32_e32 v220, 1.0
	v_mov_b32_e32 v222, 0
	v_mov_b32_e32 v214, 1.0
	v_mov_b32_e32 v216, 0
	v_mov_b32_e32 v200, 1.0
	v_mov_b32_e32 v202, 0
	v_mov_b32_e32 v194, 1.0
	v_mov_b32_e32 v196, 0
	s_andn2_b64 vcc, exec, s[26:27]
	s_cbranch_vccnz .Lqkv_h0_nost
	v_lshl_add_u64 v[162:163], v[192:193], 3, s[80:81]
	global_load_dwordx2 v[244:245], v[162:163], off
	global_load_dwordx2 v[246:247], v[162:163], off offset:128
	global_load_dwordx2 v[248:249], v[162:163], off offset:256
	global_load_dwordx2 v[250:251], v[162:163], off offset:384
	s_waitcnt vmcnt(0)
	v_pk_mul_f32 v[244:245], v[244:245], s[64:65] op_sel_hi:[1,0]
	s_nop 0
	v_fma_f32 v245, -v244, v244, v245
	v_add_f32_e32 v245, 0x3727c5ac, v245
	v_mul_f32_e32 v164, 0x4b800000, v245
	v_cmp_gt_f32_e32 vcc, s29, v245
	s_nop 1
	v_cndmask_b32_e32 v245, v245, v164, vcc
	v_rsq_f32_e32 v245, v245
	s_nop 0
	v_mul_f32_e32 v164, 0x45800000, v245
	v_cndmask_b32_e32 v220, v245, v164, vcc
	v_mul_f32_e64 v222, v244, -v220
	v_pk_mul_f32 v[246:247], v[246:247], s[64:65] op_sel_hi:[1,0]
	s_nop 0
	v_fma_f32 v247, -v246, v246, v247
	v_add_f32_e32 v247, 0x3727c5ac, v247
	v_mul_f32_e32 v164, 0x4b800000, v247
	v_cmp_gt_f32_e32 vcc, s29, v247
	s_nop 1
	v_cndmask_b32_e32 v247, v247, v164, vcc
	v_rsq_f32_e32 v247, v247
	s_nop 0
	v_mul_f32_e32 v164, 0x45800000, v247
	v_cndmask_b32_e32 v214, v247, v164, vcc
	v_mul_f32_e64 v216, v246, -v214
	v_pk_mul_f32 v[248:249], v[248:249], s[64:65] op_sel_hi:[1,0]
	s_nop 0
	v_fma_f32 v249, -v248, v248, v249
	v_add_f32_e32 v249, 0x3727c5ac, v249
	v_mul_f32_e32 v164, 0x4b800000, v249
	v_cmp_gt_f32_e32 vcc, s29, v249
	s_nop 1
	v_cndmask_b32_e32 v249, v249, v164, vcc
	v_rsq_f32_e32 v249, v249
	s_nop 0
	v_mul_f32_e32 v164, 0x45800000, v249
	v_cndmask_b32_e32 v200, v249, v164, vcc
	v_mul_f32_e64 v202, v248, -v200
	v_pk_mul_f32 v[250:251], v[250:251], s[64:65] op_sel_hi:[1,0]
	s_nop 0
	v_fma_f32 v251, -v250, v250, v251
	v_add_f32_e32 v251, 0x3727c5ac, v251
	v_mul_f32_e32 v164, 0x4b800000, v251
	v_cmp_gt_f32_e32 vcc, s29, v251
	s_nop 1
	v_cndmask_b32_e32 v251, v251, v164, vcc
	v_rsq_f32_e32 v251, v251
	s_nop 0
	v_mul_f32_e32 v164, 0x45800000, v251
	v_cndmask_b32_e32 v194, v251, v164, vcc
	v_mul_f32_e64 v196, v250, -v194
.Lqkv_h0_nost:
.LBB0_605:
	s_add_i32 s8, s7, -6
	s_cmp_lt_u32 s8, -2
	s_cselect_b64 s[36:37], -1, 0
	s_cmp_gt_u32 s8, -3
	s_cselect_b64 s[42:43], -1, 0
	s_and_b64 vcc, exec, s[42:43]
	s_cbranch_vccnz .LBB0_607
	v_lshlrev_b64 v[162:163], 7, v[192:193]
	v_lshl_add_u64 v[162:163], v[184:185], 0, v[162:163]
	global_load_dwordx4 v[174:177], v[162:163], off
	s_branch .LBB0_608
